# prologue weight-conversion: the eight row-scale loads of an item issued together after its data loads (was two at a time with a wait per pair)
# baseline (speedup 1.0000x reference)
; #define LAS __attribute__((address_space(3)))
; __device__ __forceinline__ void tr_item(const float* W, int ldn, int k0, int n0, const float* ks, const float* ns, bf16_t* WT, size_t dld, int rbase, int rstride, int dcol0, LAS float* scr, int lane) {
;     f32x4 v[8];
; #pragma unroll
;     for (int i = 0; i < 8; ++i) v[i] = *(const f32x4*)(W + (size_t)(k0 + 8 * i + (lane >> 3)) * ldn + n0 + 4 * (lane & 7));
; #pragma unroll
;     for (int i = 0; i < 8; ++i) { const int kk = 8 * i + (lane >> 3); const float s = ks ? ks[k0 + kk] : 1.0f; LAS float* d = scr + kk * 33 + 4 * (lane & 7);
;         d[0] = v[i][0] * s; d[1] = v[i][1] * s; d[2] = v[i][2] * s; d[3] = v[i][3] * s; }
.LBB0_75:
	s_lshl_b32 s30, s62, 6
	v_add_u32_e32 v42, s30, v34
	v_mad_u64_u32 v[2:3], s[4:5], v42, s14, 0
	v_ashrrev_i32_e32 v43, 31, v42
	v_mov_b32_e32 v4, v3
	v_mad_u64_u32 v[4:5], s[4:5], v43, s14, v[4:5]
	v_mov_b32_e32 v3, v4
	v_add_u32_e32 v4, 8, v42
	v_ashrrev_i32_e32 v7, 31, v4
	v_mad_u64_u32 v[4:5], s[4:5], v4, s14, 0
	s_ashr_i32 s3, s2, 31
	v_mov_b32_e32 v6, v5
	v_lshl_add_u64 v[0:1], s[2:3], 2, v[40:41]
	v_mad_u64_u32 v[6:7], s[4:5], v7, s14, v[6:7]
	v_lshl_add_u64 v[2:3], v[2:3], 2, v[0:1]
	v_mov_b32_e32 v5, v6
	v_lshl_add_u64 v[4:5], v[4:5], 2, v[0:1]
	global_load_dwordx4 v[28:31], v[2:3], off nt
	global_load_dwordx4 v[24:27], v[4:5], off nt
	v_add_u32_e32 v2, 16, v42
	v_ashrrev_i32_e32 v5, 31, v2
	v_mad_u64_u32 v[2:3], s[4:5], v2, s14, 0
	v_mov_b32_e32 v4, v3
	v_mad_u64_u32 v[4:5], s[4:5], v5, s14, v[4:5]
	v_mov_b32_e32 v3, v4
	v_add_u32_e32 v4, 24, v42
	v_ashrrev_i32_e32 v7, 31, v4
	v_mad_u64_u32 v[4:5], s[4:5], v4, s14, 0
	v_mov_b32_e32 v6, v5
	v_mad_u64_u32 v[6:7], s[4:5], v7, s14, v[6:7]
	v_lshl_add_u64 v[2:3], v[2:3], 2, v[0:1]
	v_mov_b32_e32 v5, v6
	v_lshl_add_u64 v[4:5], v[4:5], 2, v[0:1]
	global_load_dwordx4 v[20:23], v[2:3], off nt
	global_load_dwordx4 v[16:19], v[4:5], off nt
	v_add_u32_e32 v2, 32, v42
	v_ashrrev_i32_e32 v5, 31, v2
	v_mad_u64_u32 v[2:3], s[4:5], v2, s14, 0
	v_mov_b32_e32 v4, v3
	v_mad_u64_u32 v[4:5], s[4:5], v5, s14, v[4:5]
	v_mov_b32_e32 v3, v4
	v_add_u32_e32 v4, 40, v42
	v_ashrrev_i32_e32 v7, 31, v4
	v_mad_u64_u32 v[4:5], s[4:5], v4, s14, 0
	v_mov_b32_e32 v6, v5
	v_mad_u64_u32 v[6:7], s[4:5], v7, s14, v[6:7]
	v_lshl_add_u64 v[2:3], v[2:3], 2, v[0:1]
	v_mov_b32_e32 v5, v6
	v_lshl_add_u64 v[4:5], v[4:5], 2, v[0:1]
	global_load_dwordx4 v[12:15], v[2:3], off nt
	global_load_dwordx4 v[8:11], v[4:5], off nt
	v_add_u32_e32 v2, 48, v42
	v_ashrrev_i32_e32 v5, 31, v2
	v_mad_u64_u32 v[2:3], s[4:5], v2, s14, 0
	v_mov_b32_e32 v4, v3
	v_mad_u64_u32 v[4:5], s[4:5], v5, s14, v[4:5]
	v_mov_b32_e32 v3, v4
	v_add_u32_e32 v4, 56, v42
	v_ashrrev_i32_e32 v7, 31, v4
	v_mad_u64_u32 v[4:5], s[4:5], v4, s14, 0
	v_mov_b32_e32 v6, v5
	v_mad_u64_u32 v[6:7], s[4:5], v7, s14, v[6:7]
	v_mov_b32_e32 v5, v6
	v_lshl_add_u64 v[2:3], v[2:3], 2, v[0:1]
	v_lshl_add_u64 v[0:1], v[4:5], 2, v[0:1]
	global_load_dwordx4 v[4:7], v[2:3], off nt
	s_nop 0
	global_load_dwordx4 v[0:3], v[0:1], off nt
	v_mov_b32_e32 v44, 1.0
	v_cmp_ne_u32_e64 s[4:5], 1, v39
	s_andn2_b64 vcc, exec, s[24:25]
	v_mov_b32_e32 v46, 1.0
	s_cbranch_vccnz .LBB0_77
	s_ashr_i32 s31, s30, 31
	v_lshl_add_u64 v[42:43], v[42:43], 2, s[18:19]
	v_lshl_add_u64 v[50:51], s[30:31], 0, v[34:35]
	global_load_dword v42, v[42:43], off
	v_lshl_add_u64 v[50:51], v[50:51], 2, s[18:19]
	global_load_dword v46, v[50:51], off offset:32
	global_load_dword v60, v[50:51], off offset:64
	global_load_dword v62, v[50:51], off offset:96
	global_load_dword v64, v[50:51], off offset:128
	global_load_dword v66, v[50:51], off offset:160
	global_load_dword v68, v[50:51], off offset:192
	global_load_dword v70, v[50:51], off offset:224
	s_waitcnt vmcnt(7)
	v_pk_mul_f32 v[28:29], v[28:29], v[42:43] op_sel_hi:[1,0]
	v_pk_mul_f32 v[30:31], v[30:31], v[42:43] op_sel_hi:[1,0]
.LBB0_77:
	s_waitcnt vmcnt(7)
	ds_write2_b32 v47, v28, v29 offset1:1
	ds_write2_b32 v47, v30, v31 offset0:2 offset1:3
	s_waitcnt vmcnt(0)
	v_pk_mul_f32 v[24:25], v[24:25], v[46:47] op_sel_hi:[1,0]
	v_add_u32_e32 v28, 0x420, v47
	ds_write2_b32 v28, v24, v25 offset1:1
	v_pk_mul_f32 v[24:25], v[26:27], v[46:47] op_sel_hi:[1,0]
	v_add_u32_e32 v26, 0x428, v47
	s_and_b64 vcc, exec, s[4:5]
	ds_write2_b32 v26, v24, v25 offset1:1
	s_cbranch_vccnz .LBB0_79
	v_mov_b32_e32 v44, v62
	v_pk_mul_f32 v[20:21], v[20:21], v[60:61] op_sel_hi:[1,0]
	v_pk_mul_f32 v[22:23], v[22:23], v[60:61] op_sel_hi:[1,0]
.LBB0_79:
	v_add_u32_e32 v24, 0x840, v47
	ds_write2_b32 v24, v20, v21 offset1:1
	v_add_u32_e32 v20, 0x848, v47
	ds_write2_b32 v20, v22, v23 offset1:1
	s_waitcnt vmcnt(0)
	v_pk_mul_f32 v[16:17], v[16:17], v[44:45] op_sel_hi:[1,0]
	v_add_u32_e32 v20, 0xc60, v47
	ds_write2_b32 v20, v16, v17 offset1:1
	v_pk_mul_f32 v[16:17], v[18:19], v[44:45] op_sel_hi:[1,0]
	v_add_u32_e32 v18, 0xc68, v47
	s_and_b64 vcc, exec, s[4:5]
	ds_write2_b32 v18, v16, v17 offset1:1
	s_cbranch_vccnz .LBB0_81
	v_mov_b32_e32 v16, v66
	v_pk_mul_f32 v[12:13], v[12:13], v[64:65] op_sel_hi:[1,0]
	v_pk_mul_f32 v[14:15], v[14:15], v[64:65] op_sel_hi:[1,0]
	s_branch .LBB0_82

; #define LAS __attribute__((address_space(3)))
; __device__ __forceinline__ void tr_item(const float* W, int ldn, int k0, int n0, const float* ks, const float* ns, bf16_t* WT, size_t dld, int rbase, int rstride, int dcol0, LAS float* scr, int lane) {
;     ...
;     for (int i = 0; i < 8; ++i) { const int kk = 8 * i + (lane >> 3); const float s = ks ? ks[k0 + kk] : 1.0f; LAS float* d = scr + kk * 33 + 4 * (lane & 7);
;         d[0] = v[i][0] * s; d[1] = v[i][1] * s; d[2] = v[i][2] * s; d[3] = v[i][3] * s; }
.LBB0_82:
	v_add_u32_e32 v17, 0x1080, v47
	ds_write2_b32 v17, v12, v13 offset1:1
	v_add_u32_e32 v12, 0x1088, v47
	ds_write2_b32 v12, v14, v15 offset1:1
	s_waitcnt vmcnt(0)
	v_pk_mul_f32 v[8:9], v[8:9], v[16:17] op_sel_hi:[1,0]
	v_add_u32_e32 v12, 0x14a0, v47
	ds_write2_b32 v12, v8, v9 offset1:1
	v_pk_mul_f32 v[8:9], v[10:11], v[16:17] op_sel_hi:[1,0]
	v_add_u32_e32 v10, 0x14a8, v47
	s_and_b64 vcc, exec, s[24:25]
	ds_write2_b32 v10, v8, v9 offset1:1
	s_cbranch_vccz .LBB0_93
	v_mov_b32_e32 v8, v70
	v_pk_mul_f32 v[4:5], v[4:5], v[68:69] op_sel_hi:[1,0]
	v_pk_mul_f32 v[6:7], v[6:7], v[68:69] op_sel_hi:[1,0]
	s_cbranch_execnz .LBB0_85
